# row-max of the 32 scores in all attention tile bodies: two interleaved v_max3 chains instead of one 15-deep chain with a nop after each
# speedup vs baseline: 1.0055x; 1.0055x over previous
; __device__ __forceinline__ float ex2(float x) { return __builtin_amdgcn_exp2f(x); }
; __device__ __forceinline__ float half_max(float x) { auto rr = __builtin_amdgcn_permlane32_swap(__float_as_uint(x), __float_as_uint(x), false, false); return fmaxf(__uint_as_float(rr[0]), __uint_as_float(rr[1])); }
; __device__ __forceinline__ float max3f(float a, float b, float c) { float r; asm("v_max3_f32 %0, %1, %2, %3" : "=v"(r) : "v"(a), "v"(b), "v"(c)); return r; }
; template <int MODE> ...
;     ...
;         if (MODE != MODE_CMP2) {
;             float mx = max3f(s0[0], s1[0], s0[1]);
; #pragma unroll
;             for (int r = 1; r < 15; r += 2) { mx = max3f(mx, s1[r], s0[r + 1]); mx = max3f(mx, s1[r + 1], (r + 2 < 16) ? s0[r + 2] : s1[r + 1]); }
;             mx = fmaxf(mx, s1[15]);
;             mx = half_max(mx);
;             const bool minf = (m == -INFINITY);
;             if (__any((mx > RESC_THR) || (minf && mx > -INFINITY))) {
;                 const float delta = minf ? ((mx == -INFINITY) ? 0.f : mx) : fmaxf(mx, 0.f);
;                 m = (minf && mx == -INFINITY) ? -INFINITY : mref + delta;
;                 { const float nm = (m == -INFINITY) ? 0.f : -m * (1.0f / SC2);
; #pragma unroll
;                   for (int r = 0; r < 16; ++r) negm[r] = nm; }
;                 const float alpha = minf ? 1.f : ex2(-delta);
;                 l *= alpha;
;                 if (MODE != MODE_CMP1) { o[0] = o[0] * alpha; o[1] = o[1] * alpha; }
; #pragma unroll
;                 for (int r = 0; r < 16; ++r) { s0[r] -= delta; s1[r] -= delta; }
;             }
.LBB0_180:
	v_cmp_eq_f32_e64 s[0:1], s16, v142
	v_max3_f32 v0, v80, v64, v81
	v_max3_f32 v90, v72, v89, v73
	v_max3_f32 v0, v0, v65, v82
	v_max3_f32 v90, v90, v14, v74
	v_max3_f32 v0, v0, v66, v83
	v_max3_f32 v90, v90, v15, v75
	v_max3_f32 v0, v0, v67, v84
	v_max3_f32 v90, v90, v12, v76
	v_max3_f32 v0, v0, v68, v85
	v_max3_f32 v90, v90, v13, v77
	v_max3_f32 v0, v0, v69, v86
	v_max3_f32 v90, v90, v10, v78
	v_max3_f32 v0, v0, v70, v87
	v_max3_f32 v90, v90, v11, v79
	v_max3_f32 v0, v0, v71, v88
	v_max_f32_e32 v0, v0, v0
	v_max_f32_e32 v0, v0, v90
	v_mov_b32_e32 v90, v0
	s_nop 1
	v_permlane32_swap_b32_e32 v0, v90
	v_max_f32_e32 v90, v90, v90
	v_max_f32_e32 v0, v0, v0
	v_max_f32_e32 v0, v0, v90
	v_cmp_lg_f32_e64 s[40:41], s16, v0
	v_cmp_lt_f32_e32 vcc, s17, v0
	s_and_b64 s[40:41], s[0:1], s[40:41]
	s_or_b64 vcc, vcc, s[40:41]
	s_cbranch_vccz .LBB0_182
	v_cmp_eq_f32_e32 vcc, s16, v0
	v_cndmask_b32_e64 v48, v142, 0, s[0:1]
	s_nop 0
	v_cndmask_b32_e64 v49, v0, 0, vcc
	v_max_f32_e32 v0, v0, v0
	v_max_f32_e32 v0, 0, v0
	v_cndmask_b32_e64 v0, v0, v49, s[0:1]
	v_exp_f32_e64 v90, -v0
	v_add_f32_e32 v48, v48, v0
	s_and_b64 vcc, s[0:1], vcc
	v_cndmask_b32_e32 v142, v48, v220, vcc
	v_mul_f32_e32 v48, 0xc0b17218, v142
	v_cmp_neq_f32_e32 vcc, s16, v142
	v_cndmask_b32_e64 v90, v90, 1.0, s[0:1]
	v_mul_f32_e32 v140, v140, v90
	v_cndmask_b32_e32 v48, 0, v48, vcc
	v_mov_b32_e32 v49, v48
	v_mov_b32_e32 v50, v48
	v_mov_b32_e32 v51, v48
	v_mov_b32_e32 v52, v48
	v_mov_b32_e32 v53, v48
	v_mov_b32_e32 v54, v48
	v_mov_b32_e32 v55, v48
	v_mov_b32_e32 v56, v48
	v_mov_b32_e32 v57, v48
	v_mov_b32_e32 v58, v48
	v_mov_b32_e32 v59, v48
	v_mov_b32_e32 v60, v48
	v_mov_b32_e32 v61, v48
	v_mov_b32_e32 v62, v48
	v_mov_b32_e32 v63, v48
	v_pk_mul_f32 v[46:47], v[46:47], v[90:91] op_sel_hi:[1,0]
	v_pk_mul_f32 v[44:45], v[44:45], v[90:91] op_sel_hi:[1,0]
	v_pk_mul_f32 v[42:43], v[42:43], v[90:91] op_sel_hi:[1,0]
	v_pk_mul_f32 v[40:41], v[40:41], v[90:91] op_sel_hi:[1,0]
	v_pk_mul_f32 v[38:39], v[38:39], v[90:91] op_sel_hi:[1,0]
	v_pk_mul_f32 v[36:37], v[36:37], v[90:91] op_sel_hi:[1,0]
	v_pk_mul_f32 v[34:35], v[34:35], v[90:91] op_sel_hi:[1,0]
	v_pk_mul_f32 v[32:33], v[32:33], v[90:91] op_sel_hi:[1,0]
	v_pk_mul_f32 v[30:31], v[30:31], v[90:91] op_sel_hi:[1,0]
	v_pk_mul_f32 v[28:29], v[28:29], v[90:91] op_sel_hi:[1,0]
	v_pk_mul_f32 v[26:27], v[26:27], v[90:91] op_sel_hi:[1,0]
	v_pk_mul_f32 v[24:25], v[24:25], v[90:91] op_sel_hi:[1,0]
	v_pk_mul_f32 v[22:23], v[22:23], v[90:91] op_sel_hi:[1,0]
	v_pk_mul_f32 v[20:21], v[20:21], v[90:91] op_sel_hi:[1,0]
	v_pk_mul_f32 v[18:19], v[18:19], v[90:91] op_sel_hi:[1,0]
	v_pk_mul_f32 v[16:17], v[16:17], v[90:91] op_sel_hi:[1,0]
	v_pk_add_f32 v[80:81], v[80:81], v[0:1] op_sel_hi:[1,0] neg_lo:[0,1] neg_hi:[0,1]
	v_pk_add_f32 v[64:65], v[64:65], v[0:1] op_sel_hi:[1,0] neg_lo:[0,1] neg_hi:[0,1]
	v_pk_add_f32 v[82:83], v[82:83], v[0:1] op_sel_hi:[1,0] neg_lo:[0,1] neg_hi:[0,1]
	v_pk_add_f32 v[66:67], v[66:67], v[0:1] op_sel_hi:[1,0] neg_lo:[0,1] neg_hi:[0,1]
	v_pk_add_f32 v[84:85], v[84:85], v[0:1] op_sel_hi:[1,0] neg_lo:[0,1] neg_hi:[0,1]
	v_pk_add_f32 v[68:69], v[68:69], v[0:1] op_sel_hi:[1,0] neg_lo:[0,1] neg_hi:[0,1]
	v_pk_add_f32 v[86:87], v[86:87], v[0:1] op_sel_hi:[1,0] neg_lo:[0,1] neg_hi:[0,1]
	v_pk_add_f32 v[70:71], v[70:71], v[0:1] op_sel_hi:[1,0] neg_lo:[0,1] neg_hi:[0,1]
	v_pk_add_f32 v[88:89], v[88:89], v[0:1] op_sel_hi:[1,0] neg_lo:[0,1] neg_hi:[0,1]
	v_pk_add_f32 v[72:73], v[72:73], v[0:1] op_sel_hi:[1,0] neg_lo:[0,1] neg_hi:[0,1]
	v_pk_add_f32 v[14:15], v[14:15], v[0:1] op_sel_hi:[1,0] neg_lo:[0,1] neg_hi:[0,1]
	v_pk_add_f32 v[74:75], v[74:75], v[0:1] op_sel_hi:[1,0] neg_lo:[0,1] neg_hi:[0,1]
	v_pk_add_f32 v[12:13], v[12:13], v[0:1] op_sel_hi:[1,0] neg_lo:[0,1] neg_hi:[0,1]
	v_pk_add_f32 v[76:77], v[76:77], v[0:1] op_sel_hi:[1,0] neg_lo:[0,1] neg_hi:[0,1]
	v_pk_add_f32 v[10:11], v[10:11], v[0:1] op_sel_hi:[1,0] neg_lo:[0,1] neg_hi:[0,1]
	v_pk_add_f32 v[78:79], v[78:79], v[0:1] op_sel_hi:[1,0] neg_lo:[0,1] neg_hi:[0,1]

; __device__ __forceinline__ float ex2(float x) { return __builtin_amdgcn_exp2f(x); }
; __device__ __forceinline__ float half_max(float x) { auto rr = __builtin_amdgcn_permlane32_swap(__float_as_uint(x), __float_as_uint(x), false, false); return fmaxf(__uint_as_float(rr[0]), __uint_as_float(rr[1])); }
; __device__ __forceinline__ float max3f(float a, float b, float c) { float r; asm("v_max3_f32 %0, %1, %2, %3" : "=v"(r) : "v"(a), "v"(b), "v"(c)); return r; }
; template <int MODE> ...
;     ...
;         if (MODE != MODE_CMP2) {
;             float mx = max3f(s0[0], s1[0], s0[1]);
; #pragma unroll
;             for (int r = 1; r < 15; r += 2) { mx = max3f(mx, s1[r], s0[r + 1]); mx = max3f(mx, s1[r + 1], (r + 2 < 16) ? s0[r + 2] : s1[r + 1]); }
;             mx = fmaxf(mx, s1[15]);
;             mx = half_max(mx);
;             const bool minf = (m == -INFINITY);
;             if (__any((mx > RESC_THR) || (minf && mx > -INFINITY))) {
;                 const float delta = minf ? ((mx == -INFINITY) ? 0.f : mx) : fmaxf(mx, 0.f);
;                 m = (minf && mx == -INFINITY) ? -INFINITY : mref + delta;
;                 { const float nm = (m == -INFINITY) ? 0.f : -m * (1.0f / SC2);
; #pragma unroll
;                   for (int r = 0; r < 16; ++r) negm[r] = nm; }
;                 const float alpha = minf ? 1.f : ex2(-delta);
;                 l *= alpha;
;                 if (MODE != MODE_CMP1) { o[0] = o[0] * alpha; o[1] = o[1] * alpha; }
; #pragma unroll
;                 for (int r = 0; r < 16; ++r) { s0[r] -= delta; s1[r] -= delta; }
;             }
.LBB0_221:
	s_or_b64 exec, exec, s[0:1]
	s_nop 5
	v_cmp_eq_f32_e64 s[0:1], s16, v148
	v_max3_f32 v18, v34, v50, v35
	v_max3_f32 v19, v58, v43, v59
	v_max3_f32 v18, v18, v51, v36
	v_max3_f32 v19, v19, v44, v60
	v_max3_f32 v18, v18, v52, v37
	v_max3_f32 v19, v19, v45, v61
	v_max3_f32 v18, v18, v53, v38
	v_max3_f32 v19, v19, v46, v62
	v_max3_f32 v18, v18, v54, v39
	v_max3_f32 v19, v19, v47, v63
	v_max3_f32 v18, v18, v55, v40
	v_max3_f32 v19, v19, v48, v64
	v_max3_f32 v18, v18, v56, v41
	v_max3_f32 v19, v19, v49, v65
	v_max3_f32 v18, v18, v57, v42
	v_max_f32_e32 v18, v18, v18
	v_max_f32_e32 v18, v18, v19
	v_mov_b32_e32 v19, v18
	s_nop 1
	v_permlane32_swap_b32_e32 v18, v19
	v_max_f32_e32 v19, v19, v19
	v_max_f32_e32 v18, v18, v18
	v_max_f32_e32 v18, v18, v19
	v_cmp_lg_f32_e64 s[38:39], s16, v18
	v_cmp_lt_f32_e32 vcc, s17, v18
	s_and_b64 s[38:39], s[0:1], s[38:39]
	s_or_b64 vcc, vcc, s[38:39]
	s_cbranch_vccz .LBB0_238
	v_cmp_eq_f32_e32 vcc, s16, v18
	v_max_f32_e32 v4, v18, v18
	v_max_f32_e32 v4, 0, v4
	v_cndmask_b32_e64 v2, v18, 0, vcc
	v_cndmask_b32_e64 v3, v148, 0, s[0:1]
	v_cndmask_b32_e64 v2, v4, v2, s[0:1]
	v_add_f32_e32 v3, v3, v2
	s_and_b64 vcc, s[0:1], vcc
	v_cndmask_b32_e32 v148, v3, v220, vcc
	v_exp_f32_e64 v3, -v2
	v_mul_f32_e32 v4, 0xc0b17218, v148
	v_cmp_neq_f32_e32 vcc, s16, v148
	v_cndmask_b32_e64 v3, v3, 1.0, s[0:1]
	s_nop 0
	v_cndmask_b32_e32 v18, 0, v4, vcc
	v_mul_f32_e32 v149, v149, v3
	v_pk_add_f32 v[34:35], v[34:35], v[2:3] op_sel_hi:[1,0] neg_lo:[0,1] neg_hi:[0,1]
	v_pk_add_f32 v[50:51], v[50:51], v[2:3] op_sel_hi:[1,0] neg_lo:[0,1] neg_hi:[0,1]
	v_pk_add_f32 v[36:37], v[36:37], v[2:3] op_sel_hi:[1,0] neg_lo:[0,1] neg_hi:[0,1]
	v_pk_add_f32 v[52:53], v[52:53], v[2:3] op_sel_hi:[1,0] neg_lo:[0,1] neg_hi:[0,1]
	v_pk_add_f32 v[38:39], v[38:39], v[2:3] op_sel_hi:[1,0] neg_lo:[0,1] neg_hi:[0,1]
	v_pk_add_f32 v[54:55], v[54:55], v[2:3] op_sel_hi:[1,0] neg_lo:[0,1] neg_hi:[0,1]
	v_pk_add_f32 v[40:41], v[40:41], v[2:3] op_sel_hi:[1,0] neg_lo:[0,1] neg_hi:[0,1]
	v_pk_add_f32 v[56:57], v[56:57], v[2:3] op_sel_hi:[1,0] neg_lo:[0,1] neg_hi:[0,1]
	v_pk_add_f32 v[42:43], v[42:43], v[2:3] op_sel_hi:[1,0] neg_lo:[0,1] neg_hi:[0,1]
	v_pk_add_f32 v[58:59], v[58:59], v[2:3] op_sel_hi:[1,0] neg_lo:[0,1] neg_hi:[0,1]
	v_pk_add_f32 v[44:45], v[44:45], v[2:3] op_sel_hi:[1,0] neg_lo:[0,1] neg_hi:[0,1]
	v_pk_add_f32 v[60:61], v[60:61], v[2:3] op_sel_hi:[1,0] neg_lo:[0,1] neg_hi:[0,1]
	v_pk_add_f32 v[46:47], v[46:47], v[2:3] op_sel_hi:[1,0] neg_lo:[0,1] neg_hi:[0,1]
	v_pk_add_f32 v[62:63], v[62:63], v[2:3] op_sel_hi:[1,0] neg_lo:[0,1] neg_hi:[0,1]
	v_pk_add_f32 v[48:49], v[48:49], v[2:3] op_sel_hi:[1,0] neg_lo:[0,1] neg_hi:[0,1]
	v_pk_add_f32 v[64:65], v[64:65], v[2:3] op_sel_hi:[1,0] neg_lo:[0,1] neg_hi:[0,1]
	v_mov_b32_e32 v19, v18
	v_mov_b32_e32 v20, v18
	v_mov_b32_e32 v21, v18
	v_mov_b32_e32 v22, v18
	v_mov_b32_e32 v23, v18
	v_mov_b32_e32 v24, v18
	v_mov_b32_e32 v25, v18
	v_mov_b32_e32 v26, v18
	v_mov_b32_e32 v27, v18
	v_mov_b32_e32 v28, v18
	v_mov_b32_e32 v29, v18
	v_mov_b32_e32 v30, v18
	v_mov_b32_e32 v31, v18
	v_mov_b32_e32 v32, v18
	v_mov_b32_e32 v33, v18
	v_mov_b32_e32 v2, v18
	v_mov_b32_e32 v3, v18
	v_mov_b32_e32 v4, v18
	v_mov_b32_e32 v5, v18
	v_mov_b32_e32 v6, v18
	v_mov_b32_e32 v7, v18
	v_mov_b32_e32 v8, v18
	v_mov_b32_e32 v9, v18
	v_mov_b32_e32 v10, v18
	v_mov_b32_e32 v11, v18
	v_mov_b32_e32 v12, v18
	v_mov_b32_e32 v13, v18
	v_mov_b32_e32 v14, v18
	v_mov_b32_e32 v15, v18
	v_mov_b32_e32 v16, v18
	v_mov_b32_e32 v17, v18
	s_cmp_lt_i32 s7, 0
	s_cbranch_scc1 .LBB0_224

; __device__ __forceinline__ float ex2(float x) { return __builtin_amdgcn_exp2f(x); }
; __device__ __forceinline__ float half_max(float x) { auto rr = __builtin_amdgcn_permlane32_swap(__float_as_uint(x), __float_as_uint(x), false, false); return fmaxf(__uint_as_float(rr[0]), __uint_as_float(rr[1])); }
; __device__ __forceinline__ float max3f(float a, float b, float c) { float r; asm("v_max3_f32 %0, %1, %2, %3" : "=v"(r) : "v"(a), "v"(b), "v"(c)); return r; }
; template <int MODE> ...
;     ...
;         if (MODE != MODE_CMP2) {
;             float mx = max3f(s0[0], s1[0], s0[1]);
; #pragma unroll
;             for (int r = 1; r < 15; r += 2) { mx = max3f(mx, s1[r], s0[r + 1]); mx = max3f(mx, s1[r + 1], (r + 2 < 16) ? s0[r + 2] : s1[r + 1]); }
;             mx = fmaxf(mx, s1[15]);
;             mx = half_max(mx);
;             const bool minf = (m == -INFINITY);
;             if (__any((mx > RESC_THR) || (minf && mx > -INFINITY))) {
;                 const float delta = minf ? ((mx == -INFINITY) ? 0.f : mx) : fmaxf(mx, 0.f);
;                 m = (minf && mx == -INFINITY) ? -INFINITY : mref + delta;
;                 { const float nm = (m == -INFINITY) ? 0.f : -m * (1.0f / SC2);
; #pragma unroll
;                   for (int r = 0; r < 16; ++r) negm[r] = nm; }
;                 const float alpha = minf ? 1.f : ex2(-delta);
;                 l *= alpha;
;                 if (MODE != MODE_CMP1) { o[0] = o[0] * alpha; o[1] = o[1] * alpha; }
; #pragma unroll
;                 for (int r = 0; r < 16; ++r) { s0[r] -= delta; s1[r] -= delta; }
;             }
.LBB0_231:
	s_or_b64 exec, exec, s[0:1]
	s_nop 5
	v_cmp_eq_f32_e64 s[0:1], s16, v148
	v_max3_f32 v18, v34, v50, v35
	v_max3_f32 v19, v58, v43, v59
	v_max3_f32 v18, v18, v51, v36
	v_max3_f32 v19, v19, v44, v60
	v_max3_f32 v18, v18, v52, v37
	v_max3_f32 v19, v19, v45, v61
	v_max3_f32 v18, v18, v53, v38
	v_max3_f32 v19, v19, v46, v62
	v_max3_f32 v18, v18, v54, v39
	v_max3_f32 v19, v19, v47, v63
	v_max3_f32 v18, v18, v55, v40
	v_max3_f32 v19, v19, v48, v64
	v_max3_f32 v18, v18, v56, v41
	v_max3_f32 v19, v19, v49, v65
	v_max3_f32 v18, v18, v57, v42
	v_max_f32_e32 v18, v18, v18
	v_max_f32_e32 v18, v18, v19
	v_mov_b32_e32 v19, v18
	s_nop 1
	v_permlane32_swap_b32_e32 v18, v19
	v_max_f32_e32 v19, v19, v19
	v_max_f32_e32 v18, v18, v18
	v_max_f32_e32 v18, v18, v19
	v_cmp_lg_f32_e64 s[38:39], s16, v18
	v_cmp_lt_f32_e32 vcc, s17, v18
	s_and_b64 s[38:39], s[0:1], s[38:39]
	s_or_b64 vcc, vcc, s[38:39]
	s_cbranch_vccz .LBB0_233
	v_cmp_eq_f32_e32 vcc, s16, v18
	v_max_f32_e32 v4, v18, v18
	v_max_f32_e32 v4, 0, v4
	v_cndmask_b32_e64 v3, v18, 0, vcc
	v_cndmask_b32_e64 v4, v4, v3, s[0:1]
	v_cndmask_b32_e64 v2, v148, 0, s[0:1]
	v_exp_f32_e64 v3, -v4
	v_add_f32_e32 v2, v2, v4
	s_and_b64 vcc, s[0:1], vcc
	v_cndmask_b32_e32 v148, v2, v220, vcc
	v_mul_f32_e32 v2, 0xc0b17218, v148
	v_cmp_neq_f32_e32 vcc, s16, v148
	v_cndmask_b32_e64 v3, v3, 1.0, s[0:1]
	v_mul_f32_e32 v149, v149, v3
	v_cndmask_b32_e32 v2, 0, v2, vcc
	v_pk_add_f32 v[34:35], v[34:35], v[4:5] op_sel_hi:[1,0] neg_lo:[0,1] neg_hi:[0,1]
	v_pk_add_f32 v[50:51], v[50:51], v[4:5] op_sel_hi:[1,0] neg_lo:[0,1] neg_hi:[0,1]
	v_pk_add_f32 v[36:37], v[36:37], v[4:5] op_sel_hi:[1,0] neg_lo:[0,1] neg_hi:[0,1]
	v_pk_add_f32 v[52:53], v[52:53], v[4:5] op_sel_hi:[1,0] neg_lo:[0,1] neg_hi:[0,1]
	v_pk_add_f32 v[38:39], v[38:39], v[4:5] op_sel_hi:[1,0] neg_lo:[0,1] neg_hi:[0,1]
	v_pk_add_f32 v[54:55], v[54:55], v[4:5] op_sel_hi:[1,0] neg_lo:[0,1] neg_hi:[0,1]
	v_pk_add_f32 v[40:41], v[40:41], v[4:5] op_sel_hi:[1,0] neg_lo:[0,1] neg_hi:[0,1]
	v_pk_add_f32 v[56:57], v[56:57], v[4:5] op_sel_hi:[1,0] neg_lo:[0,1] neg_hi:[0,1]
	v_pk_add_f32 v[42:43], v[42:43], v[4:5] op_sel_hi:[1,0] neg_lo:[0,1] neg_hi:[0,1]
	v_pk_add_f32 v[58:59], v[58:59], v[4:5] op_sel_hi:[1,0] neg_lo:[0,1] neg_hi:[0,1]
	v_pk_add_f32 v[44:45], v[44:45], v[4:5] op_sel_hi:[1,0] neg_lo:[0,1] neg_hi:[0,1]
	v_pk_add_f32 v[60:61], v[60:61], v[4:5] op_sel_hi:[1,0] neg_lo:[0,1] neg_hi:[0,1]
	v_pk_add_f32 v[46:47], v[46:47], v[4:5] op_sel_hi:[1,0] neg_lo:[0,1] neg_hi:[0,1]
	v_pk_add_f32 v[62:63], v[62:63], v[4:5] op_sel_hi:[1,0] neg_lo:[0,1] neg_hi:[0,1]
	v_pk_add_f32 v[48:49], v[48:49], v[4:5] op_sel_hi:[1,0] neg_lo:[0,1] neg_hi:[0,1]
	v_pk_add_f32 v[64:65], v[64:65], v[4:5] op_sel_hi:[1,0] neg_lo:[0,1] neg_hi:[0,1]
	v_mov_b32_e32 v3, v2
	v_mov_b32_e32 v4, v2
	v_mov_b32_e32 v5, v2
	v_mov_b32_e32 v6, v2
	v_mov_b32_e32 v7, v2
	v_mov_b32_e32 v8, v2
	v_mov_b32_e32 v9, v2
	v_mov_b32_e32 v10, v2
	v_mov_b32_e32 v11, v2
	v_mov_b32_e32 v12, v2
	v_mov_b32_e32 v13, v2
	v_mov_b32_e32 v14, v2
	v_mov_b32_e32 v15, v2
	v_mov_b32_e32 v16, v2
	v_mov_b32_e32 v17, v2

; __device__ __forceinline__ float ex2(float x) { return __builtin_amdgcn_exp2f(x); }
; __device__ __forceinline__ float half_max(float x) { auto rr = __builtin_amdgcn_permlane32_swap(__float_as_uint(x), __float_as_uint(x), false, false); return fmaxf(__uint_as_float(rr[0]), __uint_as_float(rr[1])); }
; __device__ __forceinline__ float max3f(float a, float b, float c) { float r; asm("v_max3_f32 %0, %1, %2, %3" : "=v"(r) : "v"(a), "v"(b), "v"(c)); return r; }
; template <int MODE> ...
;     ...
;         if (MODE != MODE_CMP2) {
;             float mx = max3f(s0[0], s1[0], s0[1]);
; #pragma unroll
;             for (int r = 1; r < 15; r += 2) { mx = max3f(mx, s1[r], s0[r + 1]); mx = max3f(mx, s1[r + 1], (r + 2 < 16) ? s0[r + 2] : s1[r + 1]); }
;             mx = fmaxf(mx, s1[15]);
;             mx = half_max(mx);
;             const bool minf = (m == -INFINITY);
;             if (__any((mx > RESC_THR) || (minf && mx > -INFINITY))) {
;                 const float delta = minf ? ((mx == -INFINITY) ? 0.f : mx) : fmaxf(mx, 0.f);
;                 m = (minf && mx == -INFINITY) ? -INFINITY : mref + delta;
;                 { const float nm = (m == -INFINITY) ? 0.f : -m * (1.0f / SC2);
; #pragma unroll
;                   for (int r = 0; r < 16; ++r) negm[r] = nm; }
;                 const float alpha = minf ? 1.f : ex2(-delta);
;                 l *= alpha;
;                 if (MODE != MODE_CMP1) { o[0] = o[0] * alpha; o[1] = o[1] * alpha; }
; #pragma unroll
;                 for (int r = 0; r < 16; ++r) { s0[r] -= delta; s1[r] -= delta; }
;             }
.LBB0_315:
	s_or_b64 exec, exec, s[0:1]
	v_cmp_eq_f32_e64 s[0:1], s16, v189
	v_max3_f32 v0, v64, v80, v65
	v_max3_f32 v10, v88, v73, v89
	v_max3_f32 v0, v0, v81, v66
	v_max3_f32 v10, v10, v74, v90
	v_max3_f32 v0, v0, v82, v67
	v_max3_f32 v10, v10, v75, v91
	v_max3_f32 v0, v0, v83, v68
	v_max3_f32 v10, v10, v76, v92
	v_max3_f32 v0, v0, v84, v69
	v_max3_f32 v10, v10, v77, v93
	v_max3_f32 v0, v0, v85, v70
	v_max3_f32 v10, v10, v78, v94
	v_max3_f32 v0, v0, v86, v71
	v_max3_f32 v10, v10, v79, v95
	v_max3_f32 v0, v0, v87, v72
	v_max_f32_e32 v0, v0, v0
	v_max_f32_e32 v0, v0, v10
	v_mov_b32_e32 v10, v0
	s_nop 1
	v_permlane32_swap_b32_e32 v0, v10
	v_max_f32_e32 v10, v10, v10
	v_max_f32_e32 v0, v0, v0
	v_max_f32_e32 v0, v0, v10
	v_cmp_lg_f32_e64 s[38:39], s16, v0
	v_cmp_lt_f32_e32 vcc, s17, v0
	s_and_b64 s[38:39], s[0:1], s[38:39]
	s_or_b64 vcc, vcc, s[38:39]
	s_cbranch_vccz .LBB0_317
	v_cmp_eq_f32_e32 vcc, s16, v0
	v_cndmask_b32_e64 v10, v189, 0, s[0:1]
	s_nop 0
	v_cndmask_b32_e64 v11, v0, 0, vcc
	v_max_f32_e32 v0, v0, v0
	v_max_f32_e32 v0, 0, v0
	v_cndmask_b32_e64 v0, v0, v11, s[0:1]
	v_add_f32_e32 v10, v10, v0
	s_and_b64 vcc, s[0:1], vcc
	v_cndmask_b32_e32 v189, v10, v220, vcc
	v_mul_f32_e32 v10, 0xc0b17218, v189
	v_cmp_neq_f32_e32 vcc, s16, v189
	v_pk_add_f32 v[64:65], v[64:65], v[0:1] op_sel_hi:[1,0] neg_lo:[0,1] neg_hi:[0,1]
	v_pk_add_f32 v[80:81], v[80:81], v[0:1] op_sel_hi:[1,0] neg_lo:[0,1] neg_hi:[0,1]
	v_cndmask_b32_e32 v48, 0, v10, vcc
	v_exp_f32_e64 v10, -v0
	v_mov_b32_e32 v49, v48
	v_mov_b32_e32 v50, v48
	v_mov_b32_e32 v51, v48
	v_cndmask_b32_e64 v10, v10, 1.0, s[0:1]
	v_mov_b32_e32 v52, v48
	v_mov_b32_e32 v53, v48
	v_mov_b32_e32 v54, v48
	v_mov_b32_e32 v55, v48
	v_mov_b32_e32 v56, v48
	v_mov_b32_e32 v57, v48
	v_mov_b32_e32 v58, v48
	v_mov_b32_e32 v59, v48
	v_mov_b32_e32 v60, v48
	v_mov_b32_e32 v61, v48
	v_mov_b32_e32 v62, v48
	v_mov_b32_e32 v63, v48
	v_mul_f32_e32 v178, v178, v10
	v_pk_mul_f32 v[46:47], v[46:47], v[10:11] op_sel_hi:[1,0]
	v_pk_mul_f32 v[44:45], v[44:45], v[10:11] op_sel_hi:[1,0]
	v_pk_mul_f32 v[42:43], v[42:43], v[10:11] op_sel_hi:[1,0]
	v_pk_mul_f32 v[40:41], v[40:41], v[10:11] op_sel_hi:[1,0]
	v_pk_mul_f32 v[38:39], v[38:39], v[10:11] op_sel_hi:[1,0]
	v_pk_mul_f32 v[36:37], v[36:37], v[10:11] op_sel_hi:[1,0]
	v_pk_mul_f32 v[34:35], v[34:35], v[10:11] op_sel_hi:[1,0]
	v_pk_mul_f32 v[32:33], v[32:33], v[10:11] op_sel_hi:[1,0]
	v_pk_mul_f32 v[30:31], v[30:31], v[10:11] op_sel_hi:[1,0]
	v_pk_mul_f32 v[28:29], v[28:29], v[10:11] op_sel_hi:[1,0]
	v_pk_mul_f32 v[26:27], v[26:27], v[10:11] op_sel_hi:[1,0]
	v_pk_mul_f32 v[24:25], v[24:25], v[10:11] op_sel_hi:[1,0]
	v_pk_mul_f32 v[22:23], v[22:23], v[10:11] op_sel_hi:[1,0]
	v_pk_mul_f32 v[20:21], v[20:21], v[10:11] op_sel_hi:[1,0]
	v_pk_mul_f32 v[18:19], v[18:19], v[10:11] op_sel_hi:[1,0]
	v_pk_mul_f32 v[16:17], v[16:17], v[10:11] op_sel_hi:[1,0]
	v_pk_add_f32 v[66:67], v[66:67], v[0:1] op_sel_hi:[1,0] neg_lo:[0,1] neg_hi:[0,1]
	v_pk_add_f32 v[82:83], v[82:83], v[0:1] op_sel_hi:[1,0] neg_lo:[0,1] neg_hi:[0,1]
	v_pk_add_f32 v[68:69], v[68:69], v[0:1] op_sel_hi:[1,0] neg_lo:[0,1] neg_hi:[0,1]
	v_pk_add_f32 v[84:85], v[84:85], v[0:1] op_sel_hi:[1,0] neg_lo:[0,1] neg_hi:[0,1]
	v_pk_add_f32 v[70:71], v[70:71], v[0:1] op_sel_hi:[1,0] neg_lo:[0,1] neg_hi:[0,1]
	v_pk_add_f32 v[86:87], v[86:87], v[0:1] op_sel_hi:[1,0] neg_lo:[0,1] neg_hi:[0,1]
	v_pk_add_f32 v[72:73], v[72:73], v[0:1] op_sel_hi:[1,0] neg_lo:[0,1] neg_hi:[0,1]
	v_pk_add_f32 v[88:89], v[88:89], v[0:1] op_sel_hi:[1,0] neg_lo:[0,1] neg_hi:[0,1]
	v_pk_add_f32 v[74:75], v[74:75], v[0:1] op_sel_hi:[1,0] neg_lo:[0,1] neg_hi:[0,1]
	v_pk_add_f32 v[90:91], v[90:91], v[0:1] op_sel_hi:[1,0] neg_lo:[0,1] neg_hi:[0,1]
	v_pk_add_f32 v[76:77], v[76:77], v[0:1] op_sel_hi:[1,0] neg_lo:[0,1] neg_hi:[0,1]
	v_pk_add_f32 v[92:93], v[92:93], v[0:1] op_sel_hi:[1,0] neg_lo:[0,1] neg_hi:[0,1]
	v_pk_add_f32 v[78:79], v[78:79], v[0:1] op_sel_hi:[1,0] neg_lo:[0,1] neg_hi:[0,1]
	v_pk_add_f32 v[94:95], v[94:95], v[0:1] op_sel_hi:[1,0] neg_lo:[0,1] neg_hi:[0,1]

; __device__ __forceinline__ float ex2(float x) { return __builtin_amdgcn_exp2f(x); }
; __device__ __forceinline__ float half_max(float x) { auto rr = __builtin_amdgcn_permlane32_swap(__float_as_uint(x), __float_as_uint(x), false, false); return fmaxf(__uint_as_float(rr[0]), __uint_as_float(rr[1])); }
; __device__ __forceinline__ float max3f(float a, float b, float c) { float r; asm("v_max3_f32 %0, %1, %2, %3" : "=v"(r) : "v"(a), "v"(b), "v"(c)); return r; }
; template <int MODE> ...
;     ...
;         if (MODE != MODE_CMP2) {
;             float mx = max3f(s0[0], s1[0], s0[1]);
; #pragma unroll
;             for (int r = 1; r < 15; r += 2) { mx = max3f(mx, s1[r], s0[r + 1]); mx = max3f(mx, s1[r + 1], (r + 2 < 16) ? s0[r + 2] : s1[r + 1]); }
;             mx = fmaxf(mx, s1[15]);
;             mx = half_max(mx);
;             const bool minf = (m == -INFINITY);
;             if (__any((mx > RESC_THR) || (minf && mx > -INFINITY))) {
;                 const float delta = minf ? ((mx == -INFINITY) ? 0.f : mx) : fmaxf(mx, 0.f);
;                 m = (minf && mx == -INFINITY) ? -INFINITY : mref + delta;
;                 { const float nm = (m == -INFINITY) ? 0.f : -m * (1.0f / SC2);
; #pragma unroll
;                   for (int r = 0; r < 16; ++r) negm[r] = nm; }
;                 const float alpha = minf ? 1.f : ex2(-delta);
;                 l *= alpha;
;                 if (MODE != MODE_CMP1) { o[0] = o[0] * alpha; o[1] = o[1] * alpha; }
; #pragma unroll
;                 for (int r = 0; r < 16; ++r) { s0[r] -= delta; s1[r] -= delta; }
;             }
.LBB0_381:
	s_or_b64 exec, exec, s[0:1]
	v_cmp_eq_f32_e64 s[0:1], s16, v194
	v_max3_f32 v0, v96, v80, v97
	v_max3_f32 v10, v88, v105, v89
	v_max3_f32 v0, v0, v81, v98
	v_max3_f32 v10, v10, v106, v90
	v_max3_f32 v0, v0, v82, v99
	v_max3_f32 v10, v10, v107, v91
	v_max3_f32 v0, v0, v83, v100
	v_max3_f32 v10, v10, v108, v92
	v_max3_f32 v0, v0, v84, v101
	v_max3_f32 v10, v10, v109, v93
	v_max3_f32 v0, v0, v85, v102
	v_max3_f32 v10, v10, v110, v94
	v_max3_f32 v0, v0, v86, v103
	v_max3_f32 v10, v10, v111, v95
	v_max3_f32 v0, v0, v87, v104
	v_max_f32_e32 v0, v0, v0
	v_max_f32_e32 v0, v0, v10
	v_mov_b32_e32 v10, v0
	s_nop 1
	v_permlane32_swap_b32_e32 v0, v10
	v_max_f32_e32 v10, v10, v10
	v_max_f32_e32 v0, v0, v0
	v_max_f32_e32 v0, v0, v10
	v_cmp_lg_f32_e64 s[38:39], s16, v0
	v_cmp_lt_f32_e32 vcc, s17, v0
	s_and_b64 s[6:7], s[0:1], s[38:39]
	s_or_b64 vcc, vcc, s[6:7]
	s_cbranch_vccz .LBB0_383
	v_cmp_eq_f32_e32 vcc, s16, v0
	v_cndmask_b32_e64 v10, v194, 0, s[0:1]
	s_nop 0
	v_cndmask_b32_e64 v11, v0, 0, vcc
	v_max_f32_e32 v0, v0, v0
	v_max_f32_e32 v0, 0, v0
	v_cndmask_b32_e64 v0, v0, v11, s[0:1]
	v_add_f32_e32 v10, v10, v0
	s_and_b64 vcc, s[0:1], vcc
	v_cndmask_b32_e32 v194, v10, v220, vcc
	v_exp_f32_e64 v10, -v0
	v_mul_f32_e32 v11, 0xc0b17218, v194
	v_cmp_neq_f32_e32 vcc, s16, v194
	v_pk_add_f32 v[96:97], v[96:97], v[0:1] op_sel_hi:[1,0] neg_lo:[0,1] neg_hi:[0,1]
	v_cndmask_b32_e64 v10, v10, 1.0, s[0:1]
	v_cndmask_b32_e32 v64, 0, v11, vcc
	v_mul_f32_e32 v188, v188, v10
	v_pk_mul_f32 v[46:47], v[46:47], v[10:11] op_sel_hi:[1,0]
	v_pk_mul_f32 v[44:45], v[44:45], v[10:11] op_sel_hi:[1,0]
	v_pk_mul_f32 v[42:43], v[42:43], v[10:11] op_sel_hi:[1,0]
	v_pk_mul_f32 v[40:41], v[40:41], v[10:11] op_sel_hi:[1,0]
	v_pk_mul_f32 v[38:39], v[38:39], v[10:11] op_sel_hi:[1,0]
	v_pk_mul_f32 v[36:37], v[36:37], v[10:11] op_sel_hi:[1,0]
	v_pk_mul_f32 v[34:35], v[34:35], v[10:11] op_sel_hi:[1,0]
	v_pk_mul_f32 v[32:33], v[32:33], v[10:11] op_sel_hi:[1,0]
	v_pk_mul_f32 v[30:31], v[30:31], v[10:11] op_sel_hi:[1,0]
	v_pk_mul_f32 v[28:29], v[28:29], v[10:11] op_sel_hi:[1,0]
	v_pk_mul_f32 v[26:27], v[26:27], v[10:11] op_sel_hi:[1,0]
	v_pk_mul_f32 v[24:25], v[24:25], v[10:11] op_sel_hi:[1,0]
	v_pk_mul_f32 v[22:23], v[22:23], v[10:11] op_sel_hi:[1,0]
	v_pk_mul_f32 v[20:21], v[20:21], v[10:11] op_sel_hi:[1,0]
	v_pk_mul_f32 v[18:19], v[18:19], v[10:11] op_sel_hi:[1,0]
	v_pk_mul_f32 v[16:17], v[16:17], v[10:11] op_sel_hi:[1,0]
	v_pk_add_f32 v[80:81], v[80:81], v[0:1] op_sel_hi:[1,0] neg_lo:[0,1] neg_hi:[0,1]
	v_pk_add_f32 v[98:99], v[98:99], v[0:1] op_sel_hi:[1,0] neg_lo:[0,1] neg_hi:[0,1]
	v_pk_add_f32 v[82:83], v[82:83], v[0:1] op_sel_hi:[1,0] neg_lo:[0,1] neg_hi:[0,1]
	v_pk_add_f32 v[100:101], v[100:101], v[0:1] op_sel_hi:[1,0] neg_lo:[0,1] neg_hi:[0,1]
	v_pk_add_f32 v[84:85], v[84:85], v[0:1] op_sel_hi:[1,0] neg_lo:[0,1] neg_hi:[0,1]
	v_pk_add_f32 v[102:103], v[102:103], v[0:1] op_sel_hi:[1,0] neg_lo:[0,1] neg_hi:[0,1]
	v_pk_add_f32 v[86:87], v[86:87], v[0:1] op_sel_hi:[1,0] neg_lo:[0,1] neg_hi:[0,1]
	v_pk_add_f32 v[104:105], v[104:105], v[0:1] op_sel_hi:[1,0] neg_lo:[0,1] neg_hi:[0,1]
	v_pk_add_f32 v[88:89], v[88:89], v[0:1] op_sel_hi:[1,0] neg_lo:[0,1] neg_hi:[0,1]
	v_pk_add_f32 v[106:107], v[106:107], v[0:1] op_sel_hi:[1,0] neg_lo:[0,1] neg_hi:[0,1]
	v_pk_add_f32 v[90:91], v[90:91], v[0:1] op_sel_hi:[1,0] neg_lo:[0,1] neg_hi:[0,1]
	v_pk_add_f32 v[108:109], v[108:109], v[0:1] op_sel_hi:[1,0] neg_lo:[0,1] neg_hi:[0,1]
	v_pk_add_f32 v[92:93], v[92:93], v[0:1] op_sel_hi:[1,0] neg_lo:[0,1] neg_hi:[0,1]
	v_pk_add_f32 v[110:111], v[110:111], v[0:1] op_sel_hi:[1,0] neg_lo:[0,1] neg_hi:[0,1]
	v_pk_add_f32 v[94:95], v[94:95], v[0:1] op_sel_hi:[1,0] neg_lo:[0,1] neg_hi:[0,1]
	v_mov_b32_e32 v65, v64
	v_mov_b32_e32 v66, v64
	v_mov_b32_e32 v67, v64
	v_mov_b32_e32 v68, v64
	v_mov_b32_e32 v69, v64
	v_mov_b32_e32 v70, v64
	v_mov_b32_e32 v71, v64
	v_mov_b32_e32 v72, v64
	v_mov_b32_e32 v73, v64
	v_mov_b32_e32 v74, v64
	v_mov_b32_e32 v75, v64
	v_mov_b32_e32 v76, v64
	v_mov_b32_e32 v77, v64
	v_mov_b32_e32 v78, v64
	v_mov_b32_e32 v79, v64
	v_mov_b32_e32 v48, v64
	v_mov_b32_e32 v49, v64
	v_mov_b32_e32 v50, v64
	v_mov_b32_e32 v51, v64
	v_mov_b32_e32 v52, v64
	v_mov_b32_e32 v53, v64
	v_mov_b32_e32 v54, v64
	v_mov_b32_e32 v55, v64
	v_mov_b32_e32 v56, v64
	v_mov_b32_e32 v57, v64
	v_mov_b32_e32 v58, v64
	v_mov_b32_e32 v59, v64
	v_mov_b32_e32 v60, v64
	v_mov_b32_e32 v61, v64
	v_mov_b32_e32 v62, v64
	v_mov_b32_e32 v63, v64
	s_branch .LBB0_384

; __device__ __forceinline__ float ex2(float x) { return __builtin_amdgcn_exp2f(x); }
; __device__ __forceinline__ float half_max(float x) { auto rr = __builtin_amdgcn_permlane32_swap(__float_as_uint(x), __float_as_uint(x), false, false); return fmaxf(__uint_as_float(rr[0]), __uint_as_float(rr[1])); }
; __device__ __forceinline__ float max3f(float a, float b, float c) { float r; asm("v_max3_f32 %0, %1, %2, %3" : "=v"(r) : "v"(a), "v"(b), "v"(c)); return r; }
; template <int MODE> ...
;     ...
;         if (MODE != MODE_CMP2) {
;             float mx = max3f(s0[0], s1[0], s0[1]);
; #pragma unroll
;             for (int r = 1; r < 15; r += 2) { mx = max3f(mx, s1[r], s0[r + 1]); mx = max3f(mx, s1[r + 1], (r + 2 < 16) ? s0[r + 2] : s1[r + 1]); }
;             mx = fmaxf(mx, s1[15]);
;             mx = half_max(mx);
;             const bool minf = (m == -INFINITY);
;             if (__any((mx > RESC_THR) || (minf && mx > -INFINITY))) {
;                 const float delta = minf ? ((mx == -INFINITY) ? 0.f : mx) : fmaxf(mx, 0.f);
;                 m = (minf && mx == -INFINITY) ? -INFINITY : mref + delta;
;                 { const float nm = (m == -INFINITY) ? 0.f : -m * (1.0f / SC2);
; #pragma unroll
;                   for (int r = 0; r < 16; ++r) negm[r] = nm; }
;                 const float alpha = minf ? 1.f : ex2(-delta);
;                 l *= alpha;
;                 if (MODE != MODE_CMP1) { o[0] = o[0] * alpha; o[1] = o[1] * alpha; }
; #pragma unroll
;                 for (int r = 0; r < 16; ++r) { s0[r] -= delta; s1[r] -= delta; }
;             }
.LBB0_426:
	s_or_b64 exec, exec, s[0:1]
	v_cmp_eq_f32_e64 s[0:1], s16, v194
	v_max3_f32 v0, v96, v80, v97
	v_max3_f32 v10, v88, v105, v89
	v_max3_f32 v0, v0, v81, v98
	v_max3_f32 v10, v10, v106, v90
	v_max3_f32 v0, v0, v82, v99
	v_max3_f32 v10, v10, v107, v91
	v_max3_f32 v0, v0, v83, v100
	v_max3_f32 v10, v10, v108, v92
	v_max3_f32 v0, v0, v84, v101
	v_max3_f32 v10, v10, v109, v93
	v_max3_f32 v0, v0, v85, v102
	v_max3_f32 v10, v10, v110, v94
	v_max3_f32 v0, v0, v86, v103
	v_max3_f32 v10, v10, v111, v95
	v_max3_f32 v0, v0, v87, v104
	v_max_f32_e32 v0, v0, v0
	v_max_f32_e32 v0, v0, v10
	v_mov_b32_e32 v10, v0
	s_nop 1
	v_permlane32_swap_b32_e32 v0, v10
	v_max_f32_e32 v10, v10, v10
	v_max_f32_e32 v0, v0, v0
	v_max_f32_e32 v0, v0, v10
	v_cmp_lg_f32_e64 s[38:39], s16, v0
	v_cmp_lt_f32_e32 vcc, s17, v0
	s_and_b64 s[6:7], s[0:1], s[38:39]
	s_or_b64 vcc, vcc, s[6:7]
	s_cbranch_vccz .LBB0_428
	v_cmp_eq_f32_e32 vcc, s16, v0
	v_cndmask_b32_e64 v10, v194, 0, s[0:1]
	s_nop 0
	v_cndmask_b32_e64 v11, v0, 0, vcc
	v_max_f32_e32 v0, v0, v0
	v_max_f32_e32 v0, 0, v0
	v_cndmask_b32_e64 v0, v0, v11, s[0:1]
	v_add_f32_e32 v10, v10, v0
	s_and_b64 vcc, s[0:1], vcc
	v_cndmask_b32_e32 v194, v10, v220, vcc
	v_exp_f32_e64 v10, -v0
	v_mul_f32_e32 v11, 0xc0b17218, v194
	v_cmp_neq_f32_e32 vcc, s16, v194
	v_pk_add_f32 v[96:97], v[96:97], v[0:1] op_sel_hi:[1,0] neg_lo:[0,1] neg_hi:[0,1]
	v_cndmask_b32_e64 v10, v10, 1.0, s[0:1]
	v_cndmask_b32_e32 v48, 0, v11, vcc
	v_mul_f32_e32 v188, v188, v10
	v_pk_mul_f32 v[46:47], v[46:47], v[10:11] op_sel_hi:[1,0]
	v_pk_mul_f32 v[44:45], v[44:45], v[10:11] op_sel_hi:[1,0]
	v_pk_mul_f32 v[42:43], v[42:43], v[10:11] op_sel_hi:[1,0]
	v_pk_mul_f32 v[40:41], v[40:41], v[10:11] op_sel_hi:[1,0]
	v_pk_mul_f32 v[38:39], v[38:39], v[10:11] op_sel_hi:[1,0]
	v_pk_mul_f32 v[36:37], v[36:37], v[10:11] op_sel_hi:[1,0]
	v_pk_mul_f32 v[34:35], v[34:35], v[10:11] op_sel_hi:[1,0]
	v_pk_mul_f32 v[32:33], v[32:33], v[10:11] op_sel_hi:[1,0]
	v_pk_mul_f32 v[30:31], v[30:31], v[10:11] op_sel_hi:[1,0]
	v_pk_mul_f32 v[28:29], v[28:29], v[10:11] op_sel_hi:[1,0]
	v_pk_mul_f32 v[26:27], v[26:27], v[10:11] op_sel_hi:[1,0]
	v_pk_mul_f32 v[24:25], v[24:25], v[10:11] op_sel_hi:[1,0]
	v_pk_mul_f32 v[22:23], v[22:23], v[10:11] op_sel_hi:[1,0]
	v_pk_mul_f32 v[20:21], v[20:21], v[10:11] op_sel_hi:[1,0]
	v_pk_mul_f32 v[18:19], v[18:19], v[10:11] op_sel_hi:[1,0]
	v_pk_mul_f32 v[16:17], v[16:17], v[10:11] op_sel_hi:[1,0]
	v_pk_add_f32 v[80:81], v[80:81], v[0:1] op_sel_hi:[1,0] neg_lo:[0,1] neg_hi:[0,1]
	v_pk_add_f32 v[98:99], v[98:99], v[0:1] op_sel_hi:[1,0] neg_lo:[0,1] neg_hi:[0,1]
	v_pk_add_f32 v[82:83], v[82:83], v[0:1] op_sel_hi:[1,0] neg_lo:[0,1] neg_hi:[0,1]
	v_pk_add_f32 v[100:101], v[100:101], v[0:1] op_sel_hi:[1,0] neg_lo:[0,1] neg_hi:[0,1]
	v_pk_add_f32 v[84:85], v[84:85], v[0:1] op_sel_hi:[1,0] neg_lo:[0,1] neg_hi:[0,1]
	v_pk_add_f32 v[102:103], v[102:103], v[0:1] op_sel_hi:[1,0] neg_lo:[0,1] neg_hi:[0,1]
	v_pk_add_f32 v[86:87], v[86:87], v[0:1] op_sel_hi:[1,0] neg_lo:[0,1] neg_hi:[0,1]
	v_pk_add_f32 v[104:105], v[104:105], v[0:1] op_sel_hi:[1,0] neg_lo:[0,1] neg_hi:[0,1]
	v_pk_add_f32 v[88:89], v[88:89], v[0:1] op_sel_hi:[1,0] neg_lo:[0,1] neg_hi:[0,1]
	v_pk_add_f32 v[106:107], v[106:107], v[0:1] op_sel_hi:[1,0] neg_lo:[0,1] neg_hi:[0,1]
	v_pk_add_f32 v[90:91], v[90:91], v[0:1] op_sel_hi:[1,0] neg_lo:[0,1] neg_hi:[0,1]
	v_pk_add_f32 v[108:109], v[108:109], v[0:1] op_sel_hi:[1,0] neg_lo:[0,1] neg_hi:[0,1]
	v_pk_add_f32 v[92:93], v[92:93], v[0:1] op_sel_hi:[1,0] neg_lo:[0,1] neg_hi:[0,1]
	v_pk_add_f32 v[110:111], v[110:111], v[0:1] op_sel_hi:[1,0] neg_lo:[0,1] neg_hi:[0,1]
	v_pk_add_f32 v[94:95], v[94:95], v[0:1] op_sel_hi:[1,0] neg_lo:[0,1] neg_hi:[0,1]
	v_mov_b32_e32 v49, v48
	v_mov_b32_e32 v50, v48
	v_mov_b32_e32 v51, v48
	v_mov_b32_e32 v52, v48
	v_mov_b32_e32 v53, v48
	v_mov_b32_e32 v54, v48
	v_mov_b32_e32 v55, v48
	v_mov_b32_e32 v56, v48
	v_mov_b32_e32 v57, v48
	v_mov_b32_e32 v58, v48
	v_mov_b32_e32 v59, v48
	v_mov_b32_e32 v60, v48
	v_mov_b32_e32 v61, v48
	v_mov_b32_e32 v62, v48
	v_mov_b32_e32 v63, v48

; __device__ __forceinline__ float half_max(float x) { auto rr = __builtin_amdgcn_permlane32_swap(__float_as_uint(x), __float_as_uint(x), false, false); return fmaxf(__uint_as_float(rr[0]), __uint_as_float(rr[1])); }
; __device__ __forceinline__ float max3f(float a, float b, float c) { float r; asm("v_max3_f32 %0, %1, %2, %3" : "=v"(r) : "v"(a), "v"(b), "v"(c)); return r; }
; template <int MODE> ...
;     ...
;         } else if (MODE == MODE_WIN || MODE == MODE_SEL) {
;             const int dbase = t - kbase;
;             const lptr tb = L + tabofs + (dbase + TAB0 - 63) * 4;
; #pragma unroll
;             for (int kb = 0; kb < 2; ++kb)
; #pragma unroll
;                 for (int a = 0; a < 4; ++a)
; #pragma unroll
;                     for (int e = 0; e < 4; ++e) {
;                         const int r = 4 * a + e, off = 32 * kb + 8 * a + e; const int d = dbase - off;
;                         const float bsv = far ? tab128 : lds_ld<float>(tb + 4 * (63 - off));
;                         const bool ok = (MODE == MODE_WIN) ? ((unsigned)d < (unsigned)W) : (selbit && d >= 0);
;                         const float sv = kb ? s1[r] : s0[r];
;                         const float x = ok ? sv * SC2 + bsv : -INFINITY;
;                         if (kb) s1[r] = x; else s0[r] = x;
;                     }
;     ...
;         if (MODE != MODE_CMP2) {
;             float mx = max3f(s0[0], s1[0], s0[1]);
; #pragma unroll
;             for (int r = 1; r < 15; r += 2) { mx = max3f(mx, s1[r], s0[r + 1]); mx = max3f(mx, s1[r + 1], (r + 2 < 16) ? s0[r + 2] : s1[r + 1]); }
;             mx = fmaxf(mx, s1[15]);
;             mx = half_max(mx);
;             const bool minf = (m == -INFINITY);
;             if (__any((mx > RESC_THR) || (minf && mx > -INFINITY))) {
.LBB0_534:
	s_or_b64 exec, exec, s[0:1]
	v_subrev_u32_e32 v126, 58, v114
	s_waitcnt lgkmcnt(0)
	v_fmac_f32_e32 v209, 0x3e38aa3b, v96
	v_cmp_gt_u32_e32 vcc, s9, v126
	v_subrev_u32_e32 v197, 57, v114
	v_fmac_f32_e32 v208, 0x3e38aa3b, v95
	v_cndmask_b32_e32 v96, v220, v209, vcc
	v_cmp_gt_u32_e32 vcc, s9, v197
	v_subrev_u32_e32 v197, 56, v114
	v_fmac_f32_e32 v207, 0x3e38aa3b, v94
	v_cndmask_b32_e32 v95, v220, v208, vcc
	v_cmp_gt_u32_e32 vcc, s9, v197
	v_subrev_u32_e32 v197, 51, v114
	v_fmac_f32_e32 v206, 0x3e38aa3b, v93
	v_cndmask_b32_e32 v94, v220, v207, vcc
	v_cmp_gt_u32_e32 vcc, s9, v197
	v_subrev_u32_e32 v197, 50, v114
	v_fmac_f32_e32 v205, 0x3e38aa3b, v92
	v_cndmask_b32_e32 v93, v220, v206, vcc
	v_cmp_gt_u32_e32 vcc, s9, v197
	v_subrev_u32_e32 v197, 49, v114
	v_fmac_f32_e32 v204, 0x3e38aa3b, v91
	v_cndmask_b32_e32 v92, v220, v205, vcc
	v_cmp_gt_u32_e32 vcc, s9, v197
	v_subrev_u32_e32 v197, 48, v114
	v_fmac_f32_e32 v203, 0x3e38aa3b, v90
	v_cndmask_b32_e32 v91, v220, v204, vcc
	v_cmp_gt_u32_e32 vcc, s9, v197
	v_subrev_u32_e32 v197, 43, v114
	v_fmac_f32_e32 v202, 0x3e38aa3b, v89
	v_cndmask_b32_e32 v90, v220, v203, vcc
	v_cmp_gt_u32_e32 vcc, s9, v197
	v_subrev_u32_e32 v197, 42, v114
	v_fmac_f32_e32 v201, 0x3e38aa3b, v88
	v_cndmask_b32_e32 v89, v220, v202, vcc
	v_cmp_gt_u32_e32 vcc, s9, v197
	v_subrev_u32_e32 v197, 41, v114
	v_fmac_f32_e32 v200, 0x3e38aa3b, v87
	v_cndmask_b32_e32 v88, v220, v201, vcc
	v_cmp_gt_u32_e32 vcc, s9, v197
	v_subrev_u32_e32 v197, 40, v114
	v_fmac_f32_e32 v198, 0x3e38aa3b, v86
	v_cndmask_b32_e32 v87, v220, v200, vcc
	v_cmp_gt_u32_e32 vcc, s9, v197
	v_subrev_u32_e32 v197, 35, v114
	v_fmac_f32_e32 v196, 0x3e38aa3b, v85
	v_cndmask_b32_e32 v86, v220, v198, vcc
	v_cmp_gt_u32_e32 vcc, s9, v197
	v_fmac_f32_e32 v195, 0x3e38aa3b, v84
	v_fmac_f32_e32 v173, 0x3e38aa3b, v83
	v_cndmask_b32_e32 v85, v220, v196, vcc
	v_subrev_u32_e32 v196, 34, v114
	v_cmp_gt_u32_e32 vcc, s9, v196
	v_subrev_u32_e32 v83, 32, v114
	v_fmac_f32_e32 v172, 0x3e38aa3b, v82
	v_cndmask_b32_e32 v84, v220, v195, vcc
	v_subrev_u32_e32 v195, 33, v114
	v_cmp_gt_u32_e32 vcc, s9, v195
	v_subrev_u32_e32 v82, 27, v114
	v_fmac_f32_e32 v194, 0x3e38aa3b, v113
	v_cndmask_b32_e32 v173, v220, v173, vcc
	v_cmp_gt_u32_e32 vcc, s9, v83
	v_fmac_f32_e32 v192, 0x3e38aa3b, v112
	v_subrev_u32_e32 v112, 25, v114
	v_cndmask_b32_e32 v172, v220, v172, vcc
	v_cmp_gt_u32_e32 vcc, s9, v82
	v_subrev_u32_e32 v82, 26, v114
	v_fmac_f32_e32 v129, 0x3e38aa3b, v111
	v_cndmask_b32_e32 v83, v220, v194, vcc
	v_cmp_gt_u32_e32 vcc, s9, v82
	v_fmac_f32_e32 v128, 0x3e38aa3b, v110
	v_fmac_f32_e32 v127, 0x3e38aa3b, v109
	v_cndmask_b32_e32 v82, v220, v192, vcc
	v_cmp_gt_u32_e32 vcc, s9, v112
	v_subrev_u32_e32 v112, 24, v114
	v_fmac_f32_e32 v125, 0x3e38aa3b, v108
	v_cndmask_b32_e32 v111, v220, v129, vcc
	v_cmp_gt_u32_e32 vcc, s9, v112
	v_subrev_u32_e32 v112, 19, v114
	v_fmac_f32_e32 v124, 0x3e38aa3b, v107
	v_cndmask_b32_e32 v110, v220, v128, vcc
	v_cmp_gt_u32_e32 vcc, s9, v112
	v_subrev_u32_e32 v112, 18, v114
	v_fmac_f32_e32 v123, 0x3e38aa3b, v106
	v_cndmask_b32_e32 v109, v220, v127, vcc
	v_cmp_gt_u32_e32 vcc, s9, v112
	v_subrev_u32_e32 v112, 17, v114
	v_fmac_f32_e32 v122, 0x3e38aa3b, v105
	v_cndmask_b32_e32 v108, v220, v125, vcc
	v_cmp_gt_u32_e32 vcc, s9, v112
	v_add_u32_e32 v112, -16, v114
	v_fmac_f32_e32 v121, 0x3e38aa3b, v104
	v_cndmask_b32_e32 v107, v220, v124, vcc
	v_cmp_gt_u32_e32 vcc, s9, v112
	v_add_u32_e32 v112, -11, v114
	v_fmac_f32_e32 v120, 0x3e38aa3b, v103
	v_cndmask_b32_e32 v106, v220, v123, vcc
	v_cmp_gt_u32_e32 vcc, s9, v112
	v_add_u32_e32 v112, -10, v114
	v_fmac_f32_e32 v119, 0x3e38aa3b, v102
	v_cndmask_b32_e32 v105, v220, v122, vcc
	v_cmp_gt_u32_e32 vcc, s9, v112
	v_add_u32_e32 v112, -9, v114
	v_fmac_f32_e32 v118, 0x3e38aa3b, v101
	v_cndmask_b32_e32 v104, v220, v121, vcc
	v_cmp_gt_u32_e32 vcc, s9, v112
	v_add_u32_e32 v112, -8, v114
	v_fmac_f32_e32 v117, 0x3e38aa3b, v100
	v_cndmask_b32_e32 v103, v220, v120, vcc
	v_cmp_gt_u32_e32 vcc, s9, v112
	v_add_u32_e32 v112, -3, v114
	v_fmac_f32_e32 v116, 0x3e38aa3b, v99
	v_cndmask_b32_e32 v102, v220, v119, vcc
	v_cmp_gt_u32_e32 vcc, s9, v112
	v_add_u32_e32 v112, -2, v114
	v_fmac_f32_e32 v115, 0x3e38aa3b, v98
	v_cndmask_b32_e32 v101, v220, v118, vcc
	v_cmp_gt_u32_e32 vcc, s9, v112
	v_add_u32_e32 v112, -1, v114
	v_subrev_u32_e32 v126, 59, v114
	v_cndmask_b32_e32 v100, v220, v117, vcc
	v_cmp_gt_u32_e32 vcc, s9, v112
	v_fmac_f32_e32 v199, 0x3e38aa3b, v97
	v_cmp_eq_f32_e64 s[0:1], s16, v177
	v_cndmask_b32_e32 v99, v220, v116, vcc
	v_cmp_gt_u32_e32 vcc, s9, v114
	s_nop 1
	v_cndmask_b32_e32 v98, v220, v115, vcc
	v_cmp_gt_u32_e32 vcc, s9, v126
	s_nop 1
	v_cndmask_b32_e32 v97, v220, v199, vcc
	v_max3_f32 v112, v98, v172, v99
	v_max3_f32 v113, v97, v90, v107
	v_max3_f32 v112, v112, v173, v100
	v_max3_f32 v113, v113, v91, v108
	v_max3_f32 v112, v112, v84, v101
	v_max3_f32 v113, v113, v92, v109
	v_max3_f32 v112, v112, v85, v102
	v_max3_f32 v113, v113, v93, v110
	v_max3_f32 v112, v112, v86, v103
	v_max3_f32 v113, v113, v94, v111
	v_max3_f32 v112, v112, v87, v104
	v_max3_f32 v113, v113, v95, v82
	v_max3_f32 v112, v112, v88, v105
	v_max3_f32 v113, v113, v96, v83
	v_max3_f32 v112, v112, v89, v106
	v_max_f32_e32 v112, v112, v112
	v_max_f32_e32 v112, v112, v113
	v_mov_b32_e32 v113, v112
	s_nop 1
	v_permlane32_swap_b32_e32 v112, v113
	v_max_f32_e32 v113, v113, v113
	v_max_f32_e32 v112, v112, v112
	v_max_f32_e32 v112, v112, v113
	v_cmp_lg_f32_e64 s[38:39], s16, v112
	v_cmp_lt_f32_e32 vcc, s17, v112
	s_and_b64 s[6:7], s[0:1], s[38:39]
	s_or_b64 vcc, vcc, s[6:7]
	s_cbranch_vccz .LBB0_567
; __device__ __forceinline__ float ex2(float x) { return __builtin_amdgcn_exp2f(x); }
; template <int MODE> ...
;     ...
;             if (__any((mx > RESC_THR) || (minf && mx > -INFINITY))) {
;                 const float delta = minf ? ((mx == -INFINITY) ? 0.f : mx) : fmaxf(mx, 0.f);
;                 m = (minf && mx == -INFINITY) ? -INFINITY : mref + delta;
;                 { const float nm = (m == -INFINITY) ? 0.f : -m * (1.0f / SC2);
; #pragma unroll
;                   for (int r = 0; r < 16; ++r) negm[r] = nm; }
;                 const float alpha = minf ? 1.f : ex2(-delta);
;                 l *= alpha;
;                 if (MODE != MODE_CMP1) { o[0] = o[0] * alpha; o[1] = o[1] * alpha; }
; #pragma unroll
;                 for (int r = 0; r < 16; ++r) { s0[r] -= delta; s1[r] -= delta; }
;             }
	v_cmp_eq_f32_e32 vcc, s16, v112
	v_max_f32_e32 v4, v112, v112
	v_max_f32_e32 v4, 0, v4
	v_cndmask_b32_e64 v3, v112, 0, vcc
	v_cndmask_b32_e64 v2, v177, 0, s[0:1]
	v_cndmask_b32_e64 v66, v4, v3, s[0:1]
	v_add_f32_e32 v2, v2, v66
	s_and_b64 vcc, s[0:1], vcc
	v_cndmask_b32_e32 v177, v2, v220, vcc
	v_exp_f32_e64 v2, -v66
	v_mul_f32_e32 v3, 0xc0b17218, v177
	v_cmp_neq_f32_e32 vcc, s16, v177
	v_pk_add_f32 v[98:99], v[98:99], v[66:67] op_sel_hi:[1,0] neg_lo:[0,1] neg_hi:[0,1]
	v_cndmask_b32_e64 v2, v2, 1.0, s[0:1]
	v_cndmask_b32_e32 v114, 0, v3, vcc
	v_mul_f32_e32 v191, v191, v2
	v_pk_mul_f32 v[32:33], v[64:65], v[2:3] op_sel_hi:[1,0]
	v_pk_mul_f32 v[30:31], v[62:63], v[2:3] op_sel_hi:[1,0]
	v_pk_mul_f32 v[28:29], v[60:61], v[2:3] op_sel_hi:[1,0]
	v_pk_mul_f32 v[26:27], v[58:59], v[2:3] op_sel_hi:[1,0]
	v_pk_mul_f32 v[24:25], v[56:57], v[2:3] op_sel_hi:[1,0]
	v_pk_mul_f32 v[22:23], v[54:55], v[2:3] op_sel_hi:[1,0]
	v_pk_mul_f32 v[20:21], v[52:53], v[2:3] op_sel_hi:[1,0]
	v_pk_mul_f32 v[18:19], v[50:51], v[2:3] op_sel_hi:[1,0]
	v_pk_mul_f32 v[16:17], v[48:49], v[2:3] op_sel_hi:[1,0]
	v_pk_mul_f32 v[14:15], v[46:47], v[2:3] op_sel_hi:[1,0]
	v_pk_mul_f32 v[12:13], v[44:45], v[2:3] op_sel_hi:[1,0]
	v_pk_mul_f32 v[10:11], v[42:43], v[2:3] op_sel_hi:[1,0]
	v_pk_mul_f32 v[8:9], v[40:41], v[2:3] op_sel_hi:[1,0]
	v_pk_mul_f32 v[6:7], v[38:39], v[2:3] op_sel_hi:[1,0]
	v_pk_mul_f32 v[4:5], v[36:37], v[2:3] op_sel_hi:[1,0]
	v_pk_mul_f32 v[2:3], v[34:35], v[2:3] op_sel_hi:[1,0]
	v_pk_add_f32 v[172:173], v[172:173], v[66:67] op_sel_hi:[1,0] neg_lo:[0,1] neg_hi:[0,1]
	v_pk_add_f32 v[100:101], v[100:101], v[66:67] op_sel_hi:[1,0] neg_lo:[0,1] neg_hi:[0,1]
	v_pk_add_f32 v[84:85], v[84:85], v[66:67] op_sel_hi:[1,0] neg_lo:[0,1] neg_hi:[0,1]
	v_pk_add_f32 v[102:103], v[102:103], v[66:67] op_sel_hi:[1,0] neg_lo:[0,1] neg_hi:[0,1]
	v_pk_add_f32 v[86:87], v[86:87], v[66:67] op_sel_hi:[1,0] neg_lo:[0,1] neg_hi:[0,1]
	v_pk_add_f32 v[104:105], v[104:105], v[66:67] op_sel_hi:[1,0] neg_lo:[0,1] neg_hi:[0,1]
	v_pk_add_f32 v[88:89], v[88:89], v[66:67] op_sel_hi:[1,0] neg_lo:[0,1] neg_hi:[0,1]
	v_pk_add_f32 v[106:107], v[106:107], v[66:67] op_sel_hi:[1,0] neg_lo:[0,1] neg_hi:[0,1]
	v_pk_add_f32 v[90:91], v[90:91], v[66:67] op_sel_hi:[1,0] neg_lo:[0,1] neg_hi:[0,1]
	v_pk_add_f32 v[108:109], v[108:109], v[66:67] op_sel_hi:[1,0] neg_lo:[0,1] neg_hi:[0,1]
	v_pk_add_f32 v[92:93], v[92:93], v[66:67] op_sel_hi:[1,0] neg_lo:[0,1] neg_hi:[0,1]
	v_pk_add_f32 v[110:111], v[110:111], v[66:67] op_sel_hi:[1,0] neg_lo:[0,1] neg_hi:[0,1]
	v_pk_add_f32 v[94:95], v[94:95], v[66:67] op_sel_hi:[1,0] neg_lo:[0,1] neg_hi:[0,1]
	v_pk_add_f32 v[82:83], v[82:83], v[66:67] op_sel_hi:[1,0] neg_lo:[0,1] neg_hi:[0,1]
	v_pk_add_f32 v[96:97], v[96:97], v[66:67] op_sel_hi:[1,0] neg_lo:[0,1] neg_hi:[0,1]
	v_mov_b32_e32 v115, v114
	v_mov_b32_e32 v116, v114
	v_mov_b32_e32 v117, v114
	v_mov_b32_e32 v118, v114
	v_mov_b32_e32 v119, v114
	v_mov_b32_e32 v120, v114
	v_mov_b32_e32 v121, v114
	v_mov_b32_e32 v122, v114
	v_mov_b32_e32 v123, v114
	v_mov_b32_e32 v124, v114
	v_mov_b32_e32 v125, v114
	v_mov_b32_e32 v126, v114
	v_mov_b32_e32 v127, v114
	v_mov_b32_e32 v128, v114
	v_mov_b32_e32 v129, v114
	v_mov_b32_e32 v66, v114
	v_mov_b32_e32 v67, v114
	v_mov_b32_e32 v68, v114
	v_mov_b32_e32 v69, v114
	v_mov_b32_e32 v70, v114
	v_mov_b32_e32 v71, v114
	v_mov_b32_e32 v72, v114
	v_mov_b32_e32 v73, v114
	v_mov_b32_e32 v74, v114
	v_mov_b32_e32 v75, v114
	v_mov_b32_e32 v76, v114
	v_mov_b32_e32 v77, v114
	v_mov_b32_e32 v78, v114
	v_mov_b32_e32 v79, v114
	v_mov_b32_e32 v80, v114
	v_mov_b32_e32 v81, v114
	s_branch .LBB0_568

; __device__ __forceinline__ float half_max(float x) { auto rr = __builtin_amdgcn_permlane32_swap(__float_as_uint(x), __float_as_uint(x), false, false); return fmaxf(__uint_as_float(rr[0]), __uint_as_float(rr[1])); }
; __device__ __forceinline__ float max3f(float a, float b, float c) { float r; asm("v_max3_f32 %0, %1, %2, %3" : "=v"(r) : "v"(a), "v"(b), "v"(c)); return r; }
; template <int MODE> ...
;     ...
;         } else if (MODE == MODE_WIN || MODE == MODE_SEL) {
;             const int dbase = t - kbase;
;             const lptr tb = L + tabofs + (dbase + TAB0 - 63) * 4;
; #pragma unroll
;             for (int kb = 0; kb < 2; ++kb)
; #pragma unroll
;                 for (int a = 0; a < 4; ++a)
; #pragma unroll
;                     for (int e = 0; e < 4; ++e) {
;                         const int r = 4 * a + e, off = 32 * kb + 8 * a + e; const int d = dbase - off;
;                         const float bsv = far ? tab128 : lds_ld<float>(tb + 4 * (63 - off));
;                         const bool ok = (MODE == MODE_WIN) ? ((unsigned)d < (unsigned)W) : (selbit && d >= 0);
;                         const float sv = kb ? s1[r] : s0[r];
;                         const float x = ok ? sv * SC2 + bsv : -INFINITY;
;                         if (kb) s1[r] = x; else s0[r] = x;
;                     }
;     ...
;         if (MODE != MODE_CMP2) {
;             float mx = max3f(s0[0], s1[0], s0[1]);
; #pragma unroll
;             for (int r = 1; r < 15; r += 2) { mx = max3f(mx, s1[r], s0[r + 1]); mx = max3f(mx, s1[r + 1], (r + 2 < 16) ? s0[r + 2] : s1[r + 1]); }
;             mx = fmaxf(mx, s1[15]);
;             mx = half_max(mx);
;             const bool minf = (m == -INFINITY);
;             if (__any((mx > RESC_THR) || (minf && mx > -INFINITY))) {
.LBB0_606:
	s_or_b64 exec, exec, s[0:1]
	v_subrev_u32_e32 v18, 58, v19
	s_waitcnt lgkmcnt(0)
	v_fmac_f32_e32 v51, 0x3e38aa3b, v128
	v_cmp_gt_u32_e32 vcc, s9, v18
	v_subrev_u32_e32 v52, 57, v19
	v_fmac_f32_e32 v21, 0x3e38aa3b, v127
	v_cndmask_b32_e32 v18, v220, v51, vcc
	v_cmp_gt_u32_e32 vcc, s9, v52
	v_subrev_u32_e32 v52, 56, v19
	v_fmac_f32_e32 v20, 0x3e38aa3b, v126
	v_cndmask_b32_e32 v21, v220, v21, vcc
	v_cmp_gt_u32_e32 vcc, s9, v52
	v_subrev_u32_e32 v52, 51, v19
	v_fmac_f32_e32 v23, 0x3e38aa3b, v125
	v_cndmask_b32_e32 v20, v220, v20, vcc
	v_cmp_gt_u32_e32 vcc, s9, v52
	v_subrev_u32_e32 v52, 50, v19
	v_fmac_f32_e32 v22, 0x3e38aa3b, v124
	v_cndmask_b32_e32 v23, v220, v23, vcc
	v_cmp_gt_u32_e32 vcc, s9, v52
	v_subrev_u32_e32 v52, 49, v19
	v_fmac_f32_e32 v25, 0x3e38aa3b, v123
	v_cndmask_b32_e32 v22, v220, v22, vcc
	v_cmp_gt_u32_e32 vcc, s9, v52
	v_subrev_u32_e32 v52, 48, v19
	v_fmac_f32_e32 v24, 0x3e38aa3b, v122
	v_cndmask_b32_e32 v25, v220, v25, vcc
	v_cmp_gt_u32_e32 vcc, s9, v52
	v_subrev_u32_e32 v52, 43, v19
	v_fmac_f32_e32 v27, 0x3e38aa3b, v121
	v_cndmask_b32_e32 v24, v220, v24, vcc
	v_cmp_gt_u32_e32 vcc, s9, v52
	v_subrev_u32_e32 v52, 42, v19
	v_fmac_f32_e32 v26, 0x3e38aa3b, v120
	v_cndmask_b32_e32 v27, v220, v27, vcc
	v_cmp_gt_u32_e32 vcc, s9, v52
	v_subrev_u32_e32 v52, 41, v19
	v_fmac_f32_e32 v29, 0x3e38aa3b, v119
	v_cndmask_b32_e32 v26, v220, v26, vcc
	v_cmp_gt_u32_e32 vcc, s9, v52
	v_subrev_u32_e32 v52, 40, v19
	v_fmac_f32_e32 v28, 0x3e38aa3b, v118
	v_cndmask_b32_e32 v29, v220, v29, vcc
	v_cmp_gt_u32_e32 vcc, s9, v52
	v_subrev_u32_e32 v52, 35, v19
	v_fmac_f32_e32 v31, 0x3e38aa3b, v117
	v_cndmask_b32_e32 v28, v220, v28, vcc
	v_cmp_gt_u32_e32 vcc, s9, v52
	v_subrev_u32_e32 v52, 34, v19
	v_fmac_f32_e32 v30, 0x3e38aa3b, v116
	v_cndmask_b32_e32 v31, v220, v31, vcc
	v_cmp_gt_u32_e32 vcc, s9, v52
	v_subrev_u32_e32 v52, 33, v19
	v_fmac_f32_e32 v33, 0x3e38aa3b, v115
	v_cndmask_b32_e32 v30, v220, v30, vcc
	v_cmp_gt_u32_e32 vcc, s9, v52
	v_subrev_u32_e32 v52, 32, v19
	v_fmac_f32_e32 v32, 0x3e38aa3b, v114
	v_cndmask_b32_e32 v33, v220, v33, vcc
	v_cmp_gt_u32_e32 vcc, s9, v52
	v_subrev_u32_e32 v52, 27, v19
	v_fmac_f32_e32 v49, 0x3e38aa3b, v17
	v_cndmask_b32_e32 v32, v220, v32, vcc
	v_cmp_gt_u32_e32 vcc, s9, v52
	v_fmac_f32_e32 v48, 0x3e38aa3b, v16
	v_fmac_f32_e32 v47, 0x3e38aa3b, v15
	v_cndmask_b32_e32 v17, v220, v49, vcc
	v_subrev_u32_e32 v49, 26, v19
	v_cmp_gt_u32_e32 vcc, s9, v49
	v_fmac_f32_e32 v46, 0x3e38aa3b, v14
	v_fmac_f32_e32 v45, 0x3e38aa3b, v13
	v_cndmask_b32_e32 v16, v220, v48, vcc
	v_subrev_u32_e32 v48, 25, v19
	v_cmp_gt_u32_e32 vcc, s9, v48
	v_fmac_f32_e32 v44, 0x3e38aa3b, v12
	v_fmac_f32_e32 v43, 0x3e38aa3b, v11
	v_cndmask_b32_e32 v15, v220, v47, vcc
	v_subrev_u32_e32 v47, 24, v19
	v_cmp_gt_u32_e32 vcc, s9, v47
	v_fmac_f32_e32 v42, 0x3e38aa3b, v10
	v_fmac_f32_e32 v41, 0x3e38aa3b, v9
	v_cndmask_b32_e32 v14, v220, v46, vcc
	v_subrev_u32_e32 v46, 19, v19
	v_cmp_gt_u32_e32 vcc, s9, v46
	v_fmac_f32_e32 v40, 0x3e38aa3b, v8
	v_fmac_f32_e32 v39, 0x3e38aa3b, v7
	v_cndmask_b32_e32 v13, v220, v45, vcc
	v_subrev_u32_e32 v45, 18, v19
	v_cmp_gt_u32_e32 vcc, s9, v45
	v_fmac_f32_e32 v38, 0x3e38aa3b, v6
	v_fmac_f32_e32 v37, 0x3e38aa3b, v5
	v_cndmask_b32_e32 v12, v220, v44, vcc
	v_subrev_u32_e32 v44, 17, v19
	v_cmp_gt_u32_e32 vcc, s9, v44
	v_fmac_f32_e32 v36, 0x3e38aa3b, v4
	v_fmac_f32_e32 v35, 0x3e38aa3b, v3
	v_cndmask_b32_e32 v11, v220, v43, vcc
	v_add_u32_e32 v43, -16, v19
	v_cmp_gt_u32_e32 vcc, s9, v43
	v_fmac_f32_e32 v34, 0x3e38aa3b, v2
	v_subrev_u32_e32 v51, 59, v19
	v_cndmask_b32_e32 v10, v220, v42, vcc
	v_add_u32_e32 v42, -11, v19
	v_cmp_gt_u32_e32 vcc, s9, v42
	v_fmac_f32_e32 v50, 0x3e38aa3b, v129
	v_cmp_eq_f32_e64 s[0:1], s16, v177
	v_cndmask_b32_e32 v9, v220, v41, vcc
	v_add_u32_e32 v41, -10, v19
	v_cmp_gt_u32_e32 vcc, s9, v41
	s_nop 1
	v_cndmask_b32_e32 v8, v220, v40, vcc
	v_add_u32_e32 v40, -9, v19
	v_cmp_gt_u32_e32 vcc, s9, v40
	s_nop 1
	v_cndmask_b32_e32 v7, v220, v39, vcc
	v_add_u32_e32 v39, -8, v19
	v_cmp_gt_u32_e32 vcc, s9, v39
	s_nop 1
	v_cndmask_b32_e32 v6, v220, v38, vcc
	v_add_u32_e32 v38, -3, v19
	v_cmp_gt_u32_e32 vcc, s9, v38
	s_nop 1
	v_cndmask_b32_e32 v5, v220, v37, vcc
	v_add_u32_e32 v37, -2, v19
	v_cmp_gt_u32_e32 vcc, s9, v37
	s_nop 1
	v_cndmask_b32_e32 v4, v220, v36, vcc
	v_add_u32_e32 v36, -1, v19
	v_cmp_gt_u32_e32 vcc, s9, v36
	s_nop 1
	v_cndmask_b32_e32 v3, v220, v35, vcc
	v_cmp_gt_u32_e32 vcc, s9, v19
	s_nop 1
	v_cndmask_b32_e32 v2, v220, v34, vcc
	v_cmp_gt_u32_e32 vcc, s9, v51
	s_nop 1
	v_cndmask_b32_e32 v19, v220, v50, vcc
	v_max3_f32 v34, v2, v32, v3
	v_max3_f32 v35, v19, v24, v11
	v_max3_f32 v34, v34, v33, v4
	v_max3_f32 v35, v35, v25, v12
	v_max3_f32 v34, v34, v30, v5
	v_max3_f32 v35, v35, v22, v13
	v_max3_f32 v34, v34, v31, v6
	v_max3_f32 v35, v35, v23, v14
	v_max3_f32 v34, v34, v28, v7
	v_max3_f32 v35, v35, v20, v15
	v_max3_f32 v34, v34, v29, v8
	v_max3_f32 v35, v35, v21, v16
	v_max3_f32 v34, v34, v26, v9
	v_max3_f32 v35, v35, v18, v17
	v_max3_f32 v34, v34, v27, v10
	v_max_f32_e32 v34, v34, v34
	v_max_f32_e32 v34, v34, v35
	v_mov_b32_e32 v35, v34
	s_nop 1
	v_permlane32_swap_b32_e32 v34, v35
	v_max_f32_e32 v35, v35, v35
	v_max_f32_e32 v34, v34, v34
	v_max_f32_e32 v34, v34, v35
	v_cmp_lg_f32_e64 s[38:39], s16, v34
	v_cmp_lt_f32_e32 vcc, s17, v34
	s_and_b64 s[38:39], s[0:1], s[38:39]
	s_or_b64 vcc, vcc, s[38:39]
	s_cbranch_vccz .LBB0_639
; __device__ __forceinline__ float ex2(float x) { return __builtin_amdgcn_exp2f(x); }
; template <int MODE> ...
;     ...
;             if (__any((mx > RESC_THR) || (minf && mx > -INFINITY))) {
;                 const float delta = minf ? ((mx == -INFINITY) ? 0.f : mx) : fmaxf(mx, 0.f);
;                 m = (minf && mx == -INFINITY) ? -INFINITY : mref + delta;
;                 { const float nm = (m == -INFINITY) ? 0.f : -m * (1.0f / SC2);
; #pragma unroll
;                   for (int r = 0; r < 16; ++r) negm[r] = nm; }
;                 const float alpha = minf ? 1.f : ex2(-delta);
;                 l *= alpha;
;                 if (MODE != MODE_CMP1) { o[0] = o[0] * alpha; o[1] = o[1] * alpha; }
; #pragma unroll
;                 for (int r = 0; r < 16; ++r) { s0[r] -= delta; s1[r] -= delta; }
;             }
	v_cmp_eq_f32_e32 vcc, s16, v34
	v_cndmask_b32_e64 v35, v177, 0, s[0:1]
	s_nop 0
	v_cndmask_b32_e64 v36, v34, 0, vcc
	v_max_f32_e32 v34, v34, v34
	v_max_f32_e32 v34, 0, v34
	v_cndmask_b32_e64 v68, v34, v36, s[0:1]
	v_add_f32_e32 v34, v35, v68
	s_and_b64 vcc, s[0:1], vcc
	v_cndmask_b32_e32 v173, v34, v220, vcc
	v_exp_f32_e64 v34, -v68
	v_mul_f32_e32 v35, 0xc0b17218, v173
	v_cmp_neq_f32_e32 vcc, s16, v173
	v_pk_add_f32 v[2:3], v[2:3], v[68:69] op_sel_hi:[1,0] neg_lo:[0,1] neg_hi:[0,1]
	v_cndmask_b32_e64 v50, v34, 1.0, s[0:1]
	v_cndmask_b32_e32 v66, 0, v35, vcc
	v_mul_f32_e32 v114, v172, v50
	v_pk_mul_f32 v[48:49], v[96:97], v[50:51] op_sel_hi:[1,0]
	v_pk_mul_f32 v[46:47], v[94:95], v[50:51] op_sel_hi:[1,0]
	v_pk_mul_f32 v[44:45], v[92:93], v[50:51] op_sel_hi:[1,0]
	v_pk_mul_f32 v[42:43], v[90:91], v[50:51] op_sel_hi:[1,0]
	v_pk_mul_f32 v[40:41], v[88:89], v[50:51] op_sel_hi:[1,0]
	v_pk_mul_f32 v[38:39], v[86:87], v[50:51] op_sel_hi:[1,0]
	v_pk_mul_f32 v[36:37], v[84:85], v[50:51] op_sel_hi:[1,0]
	v_pk_mul_f32 v[34:35], v[82:83], v[50:51] op_sel_hi:[1,0]
	v_pk_mul_f32 v[64:65], v[112:113], v[50:51] op_sel_hi:[1,0]
	v_pk_mul_f32 v[62:63], v[110:111], v[50:51] op_sel_hi:[1,0]
	v_pk_mul_f32 v[60:61], v[108:109], v[50:51] op_sel_hi:[1,0]
	v_pk_mul_f32 v[58:59], v[106:107], v[50:51] op_sel_hi:[1,0]
	v_pk_mul_f32 v[56:57], v[104:105], v[50:51] op_sel_hi:[1,0]
	v_pk_mul_f32 v[54:55], v[102:103], v[50:51] op_sel_hi:[1,0]
	v_pk_mul_f32 v[52:53], v[100:101], v[50:51] op_sel_hi:[1,0]
	v_pk_mul_f32 v[50:51], v[98:99], v[50:51] op_sel_hi:[1,0]
	v_pk_add_f32 v[32:33], v[32:33], v[68:69] op_sel_hi:[1,0] neg_lo:[0,1] neg_hi:[0,1]
	v_pk_add_f32 v[4:5], v[4:5], v[68:69] op_sel_hi:[1,0] neg_lo:[0,1] neg_hi:[0,1]
	v_pk_add_f32 v[30:31], v[30:31], v[68:69] op_sel_hi:[1,0] neg_lo:[0,1] neg_hi:[0,1]
	v_pk_add_f32 v[6:7], v[6:7], v[68:69] op_sel_hi:[1,0] neg_lo:[0,1] neg_hi:[0,1]
	v_pk_add_f32 v[28:29], v[28:29], v[68:69] op_sel_hi:[1,0] neg_lo:[0,1] neg_hi:[0,1]
	v_pk_add_f32 v[8:9], v[8:9], v[68:69] op_sel_hi:[1,0] neg_lo:[0,1] neg_hi:[0,1]
	v_pk_add_f32 v[26:27], v[26:27], v[68:69] op_sel_hi:[1,0] neg_lo:[0,1] neg_hi:[0,1]
	v_pk_add_f32 v[10:11], v[10:11], v[68:69] op_sel_hi:[1,0] neg_lo:[0,1] neg_hi:[0,1]
	v_pk_add_f32 v[24:25], v[24:25], v[68:69] op_sel_hi:[1,0] neg_lo:[0,1] neg_hi:[0,1]
	v_pk_add_f32 v[12:13], v[12:13], v[68:69] op_sel_hi:[1,0] neg_lo:[0,1] neg_hi:[0,1]
	v_pk_add_f32 v[22:23], v[22:23], v[68:69] op_sel_hi:[1,0] neg_lo:[0,1] neg_hi:[0,1]
	v_pk_add_f32 v[14:15], v[14:15], v[68:69] op_sel_hi:[1,0] neg_lo:[0,1] neg_hi:[0,1]
	v_pk_add_f32 v[20:21], v[20:21], v[68:69] op_sel_hi:[1,0] neg_lo:[0,1] neg_hi:[0,1]
	v_pk_add_f32 v[16:17], v[16:17], v[68:69] op_sel_hi:[1,0] neg_lo:[0,1] neg_hi:[0,1]
	v_pk_add_f32 v[18:19], v[18:19], v[68:69] op_sel_hi:[1,0] neg_lo:[0,1] neg_hi:[0,1]
	v_mov_b32_e32 v67, v66
	v_mov_b32_e32 v68, v66
	v_mov_b32_e32 v69, v66
	v_mov_b32_e32 v70, v66
	v_mov_b32_e32 v71, v66
	v_mov_b32_e32 v72, v66
	v_mov_b32_e32 v73, v66
	v_mov_b32_e32 v74, v66
	v_mov_b32_e32 v75, v66
	v_mov_b32_e32 v76, v66
	v_mov_b32_e32 v77, v66
	v_mov_b32_e32 v78, v66
	v_mov_b32_e32 v79, v66
	v_mov_b32_e32 v80, v66
	v_mov_b32_e32 v81, v66
	s_branch .LBB0_640
